# row phases: the 64 split-K partial loads per ctx row pair run through an 8-deep register prefetch ring with exact counted waits (compiler kept only 2-4 in flight)
# baseline (speedup 1.0000x reference)
; __device__ __forceinline__ void phase_rows(const Params& p, const RowArgs& a, int G, int wave, int lane) {
;     ...
;     for (int it = (a.ctx_only && bmaj) ? ppw : 0; it < nit; ++it) {
;         int mp;
;         if (bmaj) mp = (it < ppw) ? (gw / wpb) * (SEQ / 2) + (gw % wpb) + it * wpb : ML / 2 + gw + (it - ppw) * NGW;
;         else mp = ((a.ctx_only && !bmaj) ? ML / 2 : 0) + gw + it * NGW;
;         if (mp >= a.nrows / 2) break;
;         const int m0 = 2 * mp; const bool isl = m0 < ML; const int rb = isl ? (m0 >> 12) : 8;
;         const bool use_y = a.has_y && !(a.lat_no_y && isl);
;         const size_t xoff = isl ? (size_t)m0 * DM : (size_t)(m0 - ML) * DM;
;         const void* xrb = isl ? a.xlat : a.xctx; void* xob = isl ? a.olat : a.octx;
;         bf16_t* xn = XN + (size_t)m0 * DM;
;         const size_t moff = (size_t)rb * NMOD;
;         f32x4 v[2][4], y[2][4];
;         if (a.xin_f32) {
; #pragma unroll
;             for (int u = 0; u < 2; ++u)
; #pragma unroll
;                 for (int j = 0; j < 4; ++j) v[u][j] = *(const f32x4*)((const float*)xrb + xoff + u * DM + 8 * lane + 512 * (j >> 1) + 4 * (j & 1));
;         } else {
; #pragma unroll
;             for (int u = 0; u < 2; ++u)
; #pragma unroll
;                 for (int jb = 0; jb < 2; ++jb) { const u32x4 xw = *(const u32x4*)((const bf16_t*)xrb + xoff + u * DM + 8 * lane + 512 * jb); v[u][2 * jb] = bfx4_lo(xw); v[u][2 * jb + 1] = bfx4_hi(xw); }
;         }
;         if (use_y) {
;             if (isl || !a.ctx_split) {
; #pragma unroll
;                 for (int u = 0; u < 2; ++u)
; #pragma unroll
;                     for (int jb = 0; jb < 2; ++jb) { const u32x4 yw = *(const u32x4*)(xn + u * DM + 8 * lane + 512 * jb); y[u][2 * jb] = bfx4_lo(yw); y[u][2 * jb + 1] = bfx4_hi(yw); }
;             } else {
;                 const float* part = (const float*)p.out;
; #pragma unroll
;                 for (int u = 0; u < 2; ++u)
; #pragma unroll
;                     for (int j = 0; j < 4; ++j) { const float* pp = part + (size_t)(m0 + u - ML) * DM + 8 * lane + 512 * (j >> 1) + 4 * (j & 1); f32x4 s = *(const f32x4*)pp;
; #pragma unroll
;                         for (int k = 1; k < pg8::KSPLIT; ++k) s += *(const f32x4*)(pp + (size_t)k * MC * DM);
;                         y[u][j] = s; }
.LBB0_210:
	s_cmp_ge_i32 s11, s19
	s_mov_b64 s[0:1], -1
	s_cbranch_scc1 .LBB0_204
	s_lshl_b32 s4, s11, 1
	s_cmpk_lt_i32 s11, 0x4000
	s_cselect_b64 s[0:1], -1, 0
	s_ashr_i32 s5, s4, 31
	s_add_i32 s30, s4, 0xffff8000
	s_cmpk_gt_i32 s11, 0x3fff
	s_cselect_b64 s[8:9], -1, 0
	s_and_b64 s[6:7], s[8:9], exec
	s_cselect_b32 s7, 0, s5
	s_cselect_b32 s6, s30, s4
	s_cselect_b32 s23, s99, s79
	s_cselect_b32 s26, s98, s78
	s_lshl_b64 s[24:25], s[6:7], 11
	s_add_u32 s24, s26, s24
	s_addc_u32 s25, s23, s25
	global_load_dwordx4 v[116:119], v170, s[24:25]
	global_load_dwordx4 v[112:115], v170, s[24:25] offset:1024
	global_load_dwordx4 v[108:111], v170, s[24:25] offset:2048
	global_load_dwordx4 v[104:107], v170, s[24:25] offset:3072
	s_and_b64 vcc, exec, s[0:1]
	s_cbranch_vccnz .LBB0_213
	s_lshl_b64 s[24:25], s[30:31], 12
	v_lshl_add_u64 v[88:89], v[176:177], 0, s[24:25]
	v_mov_b32_e32 v200, v88
	v_mov_b32_e32 v201, v89
	v_add_co_u32_e32 v202, vcc, 0x800000, v200
	s_nop 1
	v_addc_co_u32_e32 v203, vcc, 0, v201, vcc
	v_add_co_u32_e32 v204, vcc, 0x800000, v202
	s_nop 1
	v_addc_co_u32_e32 v205, vcc, 0, v203, vcc
	v_add_co_u32_e32 v206, vcc, 0x800000, v204
	s_nop 1
	v_addc_co_u32_e32 v207, vcc, 0, v205, vcc
	v_add_co_u32_e32 v208, vcc, 0x800000, v206
	s_nop 1
	v_addc_co_u32_e32 v209, vcc, 0, v207, vcc
	v_add_co_u32_e32 v210, vcc, 0x800000, v208
	s_nop 1
	v_addc_co_u32_e32 v211, vcc, 0, v209, vcc
	v_add_co_u32_e32 v212, vcc, 0x800000, v210
	s_nop 1
	v_addc_co_u32_e32 v213, vcc, 0, v211, vcc
	v_add_co_u32_e32 v214, vcc, 0x800000, v212
	s_nop 1
	v_addc_co_u32_e32 v215, vcc, 0, v213, vcc
	global_load_dwordx4 v[216:219], v[200:201], off offset:16
	global_load_dwordx4 v[224:227], v[200:201], off
	global_load_dwordx4 v[228:231], v[202:203], off
	global_load_dwordx4 v[232:235], v[202:203], off offset:16
	global_load_dwordx4 v[236:239], v[204:205], off
	global_load_dwordx4 v[240:243], v[204:205], off offset:16
	global_load_dwordx4 v[244:247], v[206:207], off
	global_load_dwordx4 v[248:251], v[206:207], off offset:16
	v_add_co_u32_e32 v96, vcc, 0x800000, v88
	s_mov_b64 s[26:27], 0x800000
	v_addc_co_u32_e32 v97, vcc, 0, v89, vcc
	v_lshl_add_u64 v[94:95], v[88:89], 0, s[26:27]
	s_mov_b64 s[28:29], 0x1000000
	v_add_co_u32_e32 v122, vcc, 0x1000000, v88
	s_mov_b64 s[62:63], 0x1800000
	s_nop 0
	v_addc_co_u32_e32 v123, vcc, 0, v89, vcc
	v_add_co_u32_e32 v120, vcc, 0x1800000, v88
	v_lshl_add_u64 v[100:101], v[88:89], 0, s[62:63]
	s_nop 0
	v_addc_co_u32_e32 v121, vcc, 0, v89, vcc
	v_add_co_u32_e32 v102, vcc, 0x2000000, v88
	s_mov_b64 s[64:65], 0x2000000
	s_nop 0
	v_addc_co_u32_e32 v103, vcc, 0, v89, vcc
	v_add_co_u32_e32 v124, vcc, 0x2800000, v88
	s_mov_b64 s[68:69], 0x2800000
	s_nop 0
	v_addc_co_u32_e32 v125, vcc, 0, v89, vcc
	s_mov_b64 s[70:71], 0x3000000
	v_lshl_add_u64 v[142:143], v[88:89], 0, s[70:71]
	s_mov_b64 s[74:75], 0x3800000
	v_lshl_add_u64 v[146:147], v[88:89], 0, s[74:75]
	s_mov_b64 s[76:77], 0x800800
	s_mov_b64 s[40:41], s[34:35]
	s_mov_b64 s[34:35], 0x1000800
	s_mov_b64 s[86:87], 0x1800800
	s_mov_b64 s[94:95], 0x2000800
	s_mov_b64 s[14:15], 0x2800800
	s_mov_b32 s33, s96
	s_mov_b32 s39, s97
	s_mov_b64 s[96:97], 0x3000800
	s_mov_b64 s[36:37], 0x3800800
	s_add_i32 s30, s4, 0xffff8001
	s_lshl_b64 s[24:25], s[30:31], 12
	s_mov_b32 s23, 0x1000000
	s_waitcnt vmcnt(6)
	v_mov_b32_e32 v80, v224
	v_mov_b32_e32 v81, v225
	v_mov_b32_e32 v82, v226
	v_mov_b32_e32 v83, v227
	global_load_dwordx4 v[224:227], v[208:209], off
	s_waitcnt vmcnt(6)
	v_mov_b32_e32 v90, v228
	v_mov_b32_e32 v91, v229
	v_mov_b32_e32 v92, v230
	v_mov_b32_e32 v93, v231
	global_load_dwordx4 v[228:231], v[208:209], off offset:16
	v_pk_add_f32 v[98:99], v[82:83], v[92:93]
	v_lshl_add_u64 v[92:93], v[88:89], 0, s[28:29]
	v_pk_add_f32 v[90:91], v[80:81], v[90:91]
	s_nop 0
	s_waitcnt vmcnt(9)
	v_mov_b32_e32 v84, v216
	v_mov_b32_e32 v85, v217
	v_mov_b32_e32 v86, v218
	v_mov_b32_e32 v87, v219
	global_load_dwordx4 v[216:219], v[210:211], off
	s_waitcnt vmcnt(7)
	v_mov_b32_e32 v126, v232
	v_mov_b32_e32 v127, v233
	v_mov_b32_e32 v128, v234
	v_mov_b32_e32 v129, v235
	global_load_dwordx4 v[232:235], v[210:211], off offset:16
	v_pk_add_f32 v[86:87], v[86:87], v[128:129]
	v_pk_add_f32 v[84:85], v[84:85], v[126:127]
	s_waitcnt vmcnt(7)
	v_mov_b32_e32 v80, v236
	v_mov_b32_e32 v81, v237
	v_mov_b32_e32 v82, v238
	v_mov_b32_e32 v83, v239
	global_load_dwordx4 v[236:239], v[212:213], off
	v_pk_add_f32 v[98:99], v[98:99], v[82:83]
	v_pk_add_f32 v[90:91], v[90:91], v[80:81]
	v_lshl_add_u64 v[100:101], v[88:89], 0, s[64:65]
	s_waitcnt vmcnt(7)
	v_mov_b32_e32 v92, v240
	v_mov_b32_e32 v93, v241
	v_mov_b32_e32 v94, v242
	v_mov_b32_e32 v95, v243
	global_load_dwordx4 v[240:243], v[212:213], off offset:16
	v_pk_add_f32 v[86:87], v[86:87], v[94:95]
	v_pk_add_f32 v[84:85], v[84:85], v[92:93]
	s_waitcnt vmcnt(7)
	v_mov_b32_e32 v80, v244
	v_mov_b32_e32 v81, v245
	v_mov_b32_e32 v82, v246
	v_mov_b32_e32 v83, v247
	global_load_dwordx4 v[244:247], v[214:215], off
	v_pk_add_f32 v[98:99], v[98:99], v[82:83]
	v_pk_add_f32 v[90:91], v[90:91], v[80:81]
	v_lshl_add_u64 v[100:101], v[88:89], 0, s[68:69]
	s_waitcnt vmcnt(7)
	v_mov_b32_e32 v130, v248
	v_mov_b32_e32 v131, v249
	v_mov_b32_e32 v132, v250
	v_mov_b32_e32 v133, v251
	global_load_dwordx4 v[248:251], v[214:215], off offset:16
	v_pk_add_f32 v[86:87], v[86:87], v[132:133]
	v_pk_add_f32 v[84:85], v[84:85], v[130:131]
	s_waitcnt vmcnt(7)
	v_mov_b32_e32 v80, v224
	v_mov_b32_e32 v81, v225
	v_mov_b32_e32 v82, v226
	v_mov_b32_e32 v83, v227
	global_load_dwordx4 v[224:227], v[200:201], off offset:2064
	v_pk_add_f32 v[98:99], v[98:99], v[82:83]
	v_pk_add_f32 v[90:91], v[90:91], v[80:81]
	v_add_co_u32_e32 v100, vcc, 0x3000000, v88
	s_waitcnt vmcnt(7)
	v_mov_b32_e32 v134, v228
	v_mov_b32_e32 v135, v229
	v_mov_b32_e32 v136, v230
	v_mov_b32_e32 v137, v231
	global_load_dwordx4 v[228:231], v[200:201], off offset:2048
	v_pk_add_f32 v[86:87], v[86:87], v[136:137]
	v_addc_co_u32_e32 v101, vcc, 0, v89, vcc
	v_pk_add_f32 v[84:85], v[84:85], v[134:135]
	s_waitcnt vmcnt(7)
	v_mov_b32_e32 v80, v216
	v_mov_b32_e32 v81, v217
	v_mov_b32_e32 v82, v218
	v_mov_b32_e32 v83, v219
	global_load_dwordx4 v[216:219], v[202:203], off offset:2048
	v_pk_add_f32 v[98:99], v[98:99], v[82:83]
	v_pk_add_f32 v[90:91], v[90:91], v[80:81]
	s_nop 0
	s_waitcnt vmcnt(7)
	v_mov_b32_e32 v138, v232
	v_mov_b32_e32 v139, v233
	v_mov_b32_e32 v140, v234
	v_mov_b32_e32 v141, v235
	global_load_dwordx4 v[232:235], v[202:203], off offset:2064
	v_pk_add_f32 v[84:85], v[84:85], v[138:139]
	v_pk_add_f32 v[86:87], v[86:87], v[140:141]
	s_waitcnt vmcnt(7)
	v_mov_b32_e32 v80, v236
	v_mov_b32_e32 v81, v237
	v_mov_b32_e32 v82, v238
	v_mov_b32_e32 v83, v239
	global_load_dwordx4 v[236:239], v[204:205], off offset:2048
	v_pk_add_f32 v[150:151], v[90:91], v[80:81]
	v_add_co_u32_e32 v90, vcc, 0x3800000, v88
	v_pk_add_f32 v[98:99], v[98:99], v[82:83]
	s_nop 0
	v_addc_co_u32_e32 v91, vcc, 0, v89, vcc
	s_nop 0
	s_nop 0
	s_waitcnt vmcnt(7)
	v_mov_b32_e32 v142, v240
	v_mov_b32_e32 v143, v241
	v_mov_b32_e32 v144, v242
	v_mov_b32_e32 v145, v243
	global_load_dwordx4 v[240:243], v[204:205], off offset:2064
	v_pk_add_f32 v[84:85], v[84:85], v[142:143]
	v_pk_add_f32 v[86:87], v[86:87], v[144:145]
	s_waitcnt vmcnt(7)
	v_mov_b32_e32 v80, v244
	v_mov_b32_e32 v81, v245
	v_mov_b32_e32 v82, v246
	v_mov_b32_e32 v83, v247
	global_load_dwordx4 v[244:247], v[206:207], off offset:2048
	v_pk_add_f32 v[82:83], v[98:99], v[82:83]
	v_lshl_add_u64 v[98:99], v[88:89], 0, s[76:77]
	s_nop 0
	s_waitcnt vmcnt(7)
	v_mov_b32_e32 v146, v248
	v_mov_b32_e32 v147, v249
	v_mov_b32_e32 v148, v250
	v_mov_b32_e32 v149, v251
	global_load_dwordx4 v[248:251], v[206:207], off offset:2064
	v_pk_add_f32 v[86:87], v[86:87], v[148:149]
	v_pk_add_f32 v[84:85], v[84:85], v[146:147]
	v_pk_add_f32 v[80:81], v[150:151], v[80:81]
	s_waitcnt vmcnt(6)
	v_mov_b32_e32 v126, v228
	v_mov_b32_e32 v127, v229
	v_mov_b32_e32 v128, v230
	v_mov_b32_e32 v129, v231
	global_load_dwordx4 v[228:231], v[208:209], off offset:2048
	s_waitcnt vmcnt(6)
	v_mov_b32_e32 v130, v216
	v_mov_b32_e32 v131, v217
	v_mov_b32_e32 v132, v218
	v_mov_b32_e32 v133, v219
	global_load_dwordx4 v[216:219], v[208:209], off offset:2064
	v_pk_add_f32 v[136:137], v[126:127], v[130:131]
	v_lshl_add_u64 v[130:131], v[88:89], 0, s[34:35]
	v_pk_add_f32 v[134:135], v[128:129], v[132:133]
	s_nop 0
	s_waitcnt vmcnt(9)
	v_mov_b32_e32 v92, v224
	v_mov_b32_e32 v93, v225
	v_mov_b32_e32 v94, v226
	v_mov_b32_e32 v95, v227
	global_load_dwordx4 v[224:227], v[210:211], off offset:2048
	s_waitcnt vmcnt(7)
	v_mov_b32_e32 v96, v232
	v_mov_b32_e32 v97, v233
	v_mov_b32_e32 v98, v234
	v_mov_b32_e32 v99, v235
	global_load_dwordx4 v[232:235], v[210:211], off offset:2064
	v_pk_add_f32 v[92:93], v[92:93], v[96:97]
	v_pk_add_f32 v[94:95], v[94:95], v[98:99]
	s_waitcnt vmcnt(7)
	v_mov_b32_e32 v126, v236
	v_mov_b32_e32 v127, v237
	v_mov_b32_e32 v128, v238
	v_mov_b32_e32 v129, v239
	global_load_dwordx4 v[236:239], v[212:213], off offset:2048
	v_pk_add_f32 v[136:137], v[136:137], v[126:127]
	v_lshl_add_u64 v[126:127], v[88:89], 0, s[86:87]
	v_pk_add_f32 v[134:135], v[134:135], v[128:129]
	s_nop 0
	s_waitcnt vmcnt(7)
	v_mov_b32_e32 v130, v240
	v_mov_b32_e32 v131, v241
	v_mov_b32_e32 v132, v242
	v_mov_b32_e32 v133, v243
	global_load_dwordx4 v[240:243], v[212:213], off offset:2064
	v_pk_add_f32 v[92:93], v[92:93], v[130:131]
	v_pk_add_f32 v[94:95], v[94:95], v[132:133]
	s_waitcnt vmcnt(7)
	v_mov_b32_e32 v120, v244
	v_mov_b32_e32 v121, v245
	v_mov_b32_e32 v122, v246
	v_mov_b32_e32 v123, v247
	global_load_dwordx4 v[244:247], v[214:215], off offset:2048
	v_pk_add_f32 v[138:139], v[134:135], v[122:123]
	v_lshl_add_u64 v[134:135], v[88:89], 0, s[94:95]
	v_pk_add_f32 v[140:141], v[136:137], v[120:121]
	s_nop 0
	s_waitcnt vmcnt(7)
	v_mov_b32_e32 v126, v248
	v_mov_b32_e32 v127, v249
	v_mov_b32_e32 v128, v250
	v_mov_b32_e32 v129, v251
	global_load_dwordx4 v[248:251], v[214:215], off offset:2064
	v_pk_add_f32 v[92:93], v[92:93], v[126:127]
	v_pk_add_f32 v[94:95], v[94:95], v[128:129]
	s_waitcnt vmcnt(7)
	v_mov_b32_e32 v120, v228
	v_mov_b32_e32 v121, v229
	v_mov_b32_e32 v122, v230
	v_mov_b32_e32 v123, v231
	v_pk_add_f32 v[102:103], v[138:139], v[122:123]
	v_lshl_add_u64 v[138:139], v[88:89], 0, s[14:15]
	v_pk_add_f32 v[142:143], v[140:141], v[120:121]
	s_nop 0
	s_waitcnt vmcnt(6)
	v_mov_b32_e32 v134, v216
	v_mov_b32_e32 v135, v217
	v_mov_b32_e32 v136, v218
	v_mov_b32_e32 v137, v219
	v_pk_add_f32 v[92:93], v[92:93], v[134:135]
	v_pk_add_f32 v[94:95], v[94:95], v[136:137]
	s_waitcnt vmcnt(5)
	v_mov_b32_e32 v120, v224
	v_mov_b32_e32 v121, v225
	v_mov_b32_e32 v122, v226
	v_mov_b32_e32 v123, v227
	v_pk_add_f32 v[142:143], v[142:143], v[120:121]
	v_lshl_add_u64 v[120:121], v[88:89], 0, s[96:97]
	v_pk_add_f32 v[124:125], v[102:103], v[122:123]
	s_nop 0
	s_waitcnt vmcnt(4)
	v_mov_b32_e32 v138, v232
	v_mov_b32_e32 v139, v233
	v_mov_b32_e32 v140, v234
	v_mov_b32_e32 v141, v235
	v_pk_add_f32 v[92:93], v[92:93], v[138:139]
	v_pk_add_f32 v[94:95], v[94:95], v[140:141]
	s_waitcnt vmcnt(3)
	v_mov_b32_e32 v100, v236
	v_mov_b32_e32 v101, v237
	v_mov_b32_e32 v102, v238
	v_mov_b32_e32 v103, v239
	v_pk_add_f32 v[142:143], v[142:143], v[100:101]
	v_lshl_add_u64 v[100:101], v[88:89], 0, s[36:37]
	v_pk_add_f32 v[124:125], v[124:125], v[102:103]
	s_nop 0
	s_waitcnt vmcnt(2)
	v_mov_b32_e32 v120, v240
	v_mov_b32_e32 v121, v241
	v_mov_b32_e32 v122, v242
	v_mov_b32_e32 v123, v243
	v_pk_add_f32 v[92:93], v[92:93], v[120:121]
	v_lshl_add_u64 v[120:121], v[176:177], 0, s[24:25]
	v_pk_add_f32 v[94:95], v[94:95], v[122:123]
	v_add_co_u32_e32 v128, vcc, s55, v120
	v_lshl_add_u64 v[126:127], v[120:121], 0, s[26:27]
	s_nop 0
	v_addc_co_u32_e32 v129, vcc, 0, v121, vcc
	v_add_co_u32_e32 v132, vcc, s23, v120
	s_mov_b32 s23, 0x1800000
	s_nop 0
	v_addc_co_u32_e32 v133, vcc, 0, v121, vcc
	v_add_co_u32_e32 v136, vcc, s23, v120
	v_lshl_add_u64 v[134:135], v[120:121], 0, s[62:63]
	s_nop 0
	v_addc_co_u32_e32 v137, vcc, 0, v121, vcc
	s_brev_b32 s23, 64
	s_waitcnt vmcnt(1)
	v_mov_b32_e32 v88, v244
	v_mov_b32_e32 v89, v245
	v_mov_b32_e32 v90, v246
	v_mov_b32_e32 v91, v247
	v_pk_add_f32 v[90:91], v[124:125], v[90:91]
	s_waitcnt vmcnt(0)
	v_mov_b32_e32 v100, v248
	v_mov_b32_e32 v101, v249
	v_mov_b32_e32 v102, v250
	v_mov_b32_e32 v103, v251
	v_pk_add_f32 v[94:95], v[94:95], v[102:103]
	v_pk_add_f32 v[92:93], v[92:93], v[100:101]
	v_add_co_u32_e32 v200, vcc, 0x1000, v200
	s_nop 1
	v_addc_co_u32_e32 v201, vcc, 0, v201, vcc
	v_add_co_u32_e32 v202, vcc, 0x1000, v202
	s_nop 1
	v_addc_co_u32_e32 v203, vcc, 0, v203, vcc
	v_add_co_u32_e32 v204, vcc, 0x1000, v204
	s_nop 1
	v_addc_co_u32_e32 v205, vcc, 0, v205, vcc
	v_add_co_u32_e32 v206, vcc, 0x1000, v206
	s_nop 1
	v_addc_co_u32_e32 v207, vcc, 0, v207, vcc
	v_add_co_u32_e32 v208, vcc, 0x1000, v208
	s_nop 1
	v_addc_co_u32_e32 v209, vcc, 0, v209, vcc
	v_add_co_u32_e32 v210, vcc, 0x1000, v210
	s_nop 1
	v_addc_co_u32_e32 v211, vcc, 0, v211, vcc
	v_add_co_u32_e32 v212, vcc, 0x1000, v212
	s_nop 1
	v_addc_co_u32_e32 v213, vcc, 0, v213, vcc
	v_add_co_u32_e32 v214, vcc, 0x1000, v214
	s_nop 1
	v_addc_co_u32_e32 v215, vcc, 0, v215, vcc
	global_load_dwordx4 v[216:219], v[200:201], off offset:16
	global_load_dwordx4 v[224:227], v[200:201], off
	global_load_dwordx4 v[228:231], v[202:203], off
	global_load_dwordx4 v[232:235], v[202:203], off offset:16
	global_load_dwordx4 v[236:239], v[204:205], off
	global_load_dwordx4 v[240:243], v[204:205], off offset:16
	global_load_dwordx4 v[244:247], v[206:207], off
	global_load_dwordx4 v[248:251], v[206:207], off offset:16
	v_pk_add_f32 v[88:89], v[142:143], v[88:89]
	v_lshl_add_u64 v[142:143], v[120:121], 0, s[64:65]
	s_waitcnt vmcnt(6)
	v_mov_b32_e32 v96, v224
	v_mov_b32_e32 v97, v225
	v_mov_b32_e32 v98, v226
	v_mov_b32_e32 v99, v227
	global_load_dwordx4 v[224:227], v[208:209], off
	s_waitcnt vmcnt(6)
	v_mov_b32_e32 v122, v228
	v_mov_b32_e32 v123, v229
	v_mov_b32_e32 v124, v230
	v_mov_b32_e32 v125, v231
	global_load_dwordx4 v[228:231], v[208:209], off offset:16
	v_pk_add_f32 v[130:131], v[98:99], v[124:125]
	v_lshl_add_u64 v[124:125], v[120:121], 0, s[28:29]
	v_pk_add_f32 v[122:123], v[96:97], v[122:123]
	s_nop 0
	s_waitcnt vmcnt(9)
	v_mov_b32_e32 v100, v216
	v_mov_b32_e32 v101, v217
	v_mov_b32_e32 v102, v218
	v_mov_b32_e32 v103, v219
	global_load_dwordx4 v[216:219], v[210:211], off
	s_waitcnt vmcnt(7)
	v_mov_b32_e32 v138, v232
	v_mov_b32_e32 v139, v233
	v_mov_b32_e32 v140, v234
	v_mov_b32_e32 v141, v235
	global_load_dwordx4 v[232:235], v[210:211], off offset:16
	v_pk_add_f32 v[102:103], v[102:103], v[140:141]
	v_pk_add_f32 v[100:101], v[100:101], v[138:139]
	s_waitcnt vmcnt(7)
	v_mov_b32_e32 v96, v236
	v_mov_b32_e32 v97, v237
	v_mov_b32_e32 v98, v238
	v_mov_b32_e32 v99, v239
	global_load_dwordx4 v[236:239], v[212:213], off
	v_pk_add_f32 v[130:131], v[130:131], v[98:99]
	v_pk_add_f32 v[122:123], v[122:123], v[96:97]
	s_waitcnt vmcnt(7)
	v_mov_b32_e32 v124, v240
	v_mov_b32_e32 v125, v241
	v_mov_b32_e32 v126, v242
	v_mov_b32_e32 v127, v243
	global_load_dwordx4 v[240:243], v[212:213], off offset:16
	v_pk_add_f32 v[102:103], v[102:103], v[126:127]
	v_pk_add_f32 v[100:101], v[100:101], v[124:125]
	s_waitcnt vmcnt(7)
	v_mov_b32_e32 v96, v244
	v_mov_b32_e32 v97, v245
	v_mov_b32_e32 v98, v246
	v_mov_b32_e32 v99, v247
	global_load_dwordx4 v[244:247], v[214:215], off
	v_pk_add_f32 v[134:135], v[122:123], v[96:97]
	v_add_co_u32_e32 v122, vcc, s23, v120
	v_pk_add_f32 v[130:131], v[130:131], v[98:99]
	s_nop 0
	v_addc_co_u32_e32 v123, vcc, 0, v121, vcc
	s_mov_b32 s23, 0x2800000
	v_add_co_u32_e32 v144, vcc, s23, v120
	v_lshl_add_u64 v[142:143], v[120:121], 0, s[68:69]
	s_nop 0
	v_addc_co_u32_e32 v145, vcc, 0, v121, vcc
	s_mov_b32 s23, 0x3000000
	v_add_co_u32_e32 v148, vcc, s23, v120
	s_mov_b32 s23, 0x3800000
	s_nop 0
	v_addc_co_u32_e32 v149, vcc, 0, v121, vcc
	v_add_co_u32_e32 v152, vcc, s23, v120
	s_waitcnt vmcnt(7)
	v_mov_b32_e32 v178, v248
	v_mov_b32_e32 v179, v249
	v_mov_b32_e32 v180, v250
	v_mov_b32_e32 v181, v251
	global_load_dwordx4 v[248:251], v[214:215], off offset:16
	v_pk_add_f32 v[102:103], v[102:103], v[180:181]
	v_addc_co_u32_e32 v153, vcc, 0, v121, vcc
	v_pk_add_f32 v[100:101], v[100:101], v[178:179]
	s_waitcnt vmcnt(7)
	v_mov_b32_e32 v96, v224
	v_mov_b32_e32 v97, v225
	v_mov_b32_e32 v98, v226
	v_mov_b32_e32 v99, v227
	global_load_dwordx4 v[224:227], v[200:201], off offset:2064
	v_pk_add_f32 v[130:131], v[130:131], v[98:99]
	v_pk_add_f32 v[134:135], v[134:135], v[96:97]
	v_lshl_add_u64 v[142:143], v[120:121], 0, s[70:71]
	s_waitcnt vmcnt(7)
	v_mov_b32_e32 v182, v228
	v_mov_b32_e32 v183, v229
	v_mov_b32_e32 v184, v230
	v_mov_b32_e32 v185, v231
	global_load_dwordx4 v[228:231], v[200:201], off offset:2048
	v_pk_add_f32 v[100:101], v[100:101], v[182:183]
	v_pk_add_f32 v[102:103], v[102:103], v[184:185]
	s_waitcnt vmcnt(7)
	v_mov_b32_e32 v96, v216
	v_mov_b32_e32 v97, v217
	v_mov_b32_e32 v98, v218
	v_mov_b32_e32 v99, v219
	global_load_dwordx4 v[216:219], v[202:203], off offset:2048
	v_pk_add_f32 v[130:131], v[130:131], v[98:99]
	v_pk_add_f32 v[134:135], v[134:135], v[96:97]
	v_lshl_add_u64 v[142:143], v[120:121], 0, s[74:75]
	s_waitcnt vmcnt(7)
	v_mov_b32_e32 v186, v232
	v_mov_b32_e32 v187, v233
	v_mov_b32_e32 v188, v234
	v_mov_b32_e32 v189, v235
	global_load_dwordx4 v[232:235], v[202:203], off offset:2064
	v_pk_add_f32 v[102:103], v[102:103], v[188:189]
	v_pk_add_f32 v[100:101], v[100:101], v[186:187]
	s_waitcnt vmcnt(7)
	v_mov_b32_e32 v96, v236
	v_mov_b32_e32 v97, v237
	v_mov_b32_e32 v98, v238
	v_mov_b32_e32 v99, v239
	global_load_dwordx4 v[236:239], v[204:205], off offset:2048
	v_pk_add_f32 v[130:131], v[130:131], v[98:99]
	v_pk_add_f32 v[134:135], v[134:135], v[96:97]
	s_waitcnt vmcnt(7)
	v_mov_b32_e32 v190, v240
	v_mov_b32_e32 v191, v241
	v_mov_b32_e32 v192, v242
	v_mov_b32_e32 v193, v243
	global_load_dwordx4 v[240:243], v[204:205], off offset:2064
	v_pk_add_f32 v[102:103], v[102:103], v[192:193]
	v_pk_add_f32 v[100:101], v[100:101], v[190:191]
	s_waitcnt vmcnt(7)
	v_mov_b32_e32 v96, v244
	v_mov_b32_e32 v97, v245
	v_mov_b32_e32 v98, v246
	v_mov_b32_e32 v99, v247
	global_load_dwordx4 v[244:247], v[206:207], off offset:2048
	v_pk_add_f32 v[98:99], v[130:131], v[98:99]
	v_lshl_add_u64 v[130:131], v[120:121], 0, s[76:77]
	s_nop 0
	v_pk_add_f32 v[96:97], v[134:135], v[96:97]
	v_lshl_add_u64 v[134:135], v[120:121], 0, s[34:35]
	s_waitcnt vmcnt(7)
	v_mov_b32_e32 v194, v248
	v_mov_b32_e32 v195, v249
	v_mov_b32_e32 v196, v250
	v_mov_b32_e32 v197, v251
	global_load_dwordx4 v[248:251], v[206:207], off offset:2064
	v_pk_add_f32 v[102:103], v[102:103], v[196:197]
	v_pk_add_f32 v[100:101], v[100:101], v[194:195]
	s_mov_b64 s[34:35], s[40:41]
	s_waitcnt vmcnt(6)
	v_mov_b32_e32 v138, v228
	v_mov_b32_e32 v139, v229
	v_mov_b32_e32 v140, v230
	v_mov_b32_e32 v141, v231
	global_load_dwordx4 v[228:231], v[208:209], off offset:2048
	s_waitcnt vmcnt(6)
	v_mov_b32_e32 v178, v216
	v_mov_b32_e32 v179, v217
	v_mov_b32_e32 v180, v218
	v_mov_b32_e32 v181, v219
	global_load_dwordx4 v[216:219], v[208:209], off offset:2064
	v_pk_add_f32 v[142:143], v[140:141], v[180:181]
	v_pk_add_f32 v[146:147], v[138:139], v[178:179]
	s_nop 0
	s_waitcnt vmcnt(9)
	v_mov_b32_e32 v124, v224
	v_mov_b32_e32 v125, v225
	v_mov_b32_e32 v126, v226
	v_mov_b32_e32 v127, v227
	global_load_dwordx4 v[224:227], v[210:211], off offset:2048
	s_waitcnt vmcnt(7)
	v_mov_b32_e32 v128, v232
	v_mov_b32_e32 v129, v233
	v_mov_b32_e32 v130, v234
	v_mov_b32_e32 v131, v235
	global_load_dwordx4 v[232:235], v[210:211], off offset:2064
	v_pk_add_f32 v[126:127], v[126:127], v[130:131]
	v_pk_add_f32 v[124:125], v[124:125], v[128:129]
	s_waitcnt vmcnt(7)
	v_mov_b32_e32 v138, v236
	v_mov_b32_e32 v139, v237
	v_mov_b32_e32 v140, v238
	v_mov_b32_e32 v141, v239
	global_load_dwordx4 v[236:239], v[212:213], off offset:2048
	v_pk_add_f32 v[146:147], v[146:147], v[138:139]
	v_lshl_add_u64 v[138:139], v[120:121], 0, s[86:87]
	v_pk_add_f32 v[150:151], v[142:143], v[140:141]
	s_nop 0
	s_waitcnt vmcnt(7)
	v_mov_b32_e32 v132, v240
	v_mov_b32_e32 v133, v241
	v_mov_b32_e32 v134, v242
	v_mov_b32_e32 v135, v243
	global_load_dwordx4 v[240:243], v[212:213], off offset:2064
	v_pk_add_f32 v[126:127], v[126:127], v[134:135]
	v_pk_add_f32 v[124:125], v[124:125], v[132:133]
	s_mov_b32 s87, s38
	v_readlane_b32 s86, v255, 11
	s_waitcnt vmcnt(7)
	v_mov_b32_e32 v140, v244
	v_mov_b32_e32 v141, v245
	v_mov_b32_e32 v142, v246
	v_mov_b32_e32 v143, v247
	global_load_dwordx4 v[244:247], v[214:215], off offset:2048
	v_pk_add_f32 v[146:147], v[146:147], v[140:141]
	v_lshl_add_u64 v[140:141], v[120:121], 0, s[94:95]
	v_pk_add_f32 v[150:151], v[150:151], v[142:143]
	s_nop 0
	s_waitcnt vmcnt(7)
	v_mov_b32_e32 v136, v248
	v_mov_b32_e32 v137, v249
	v_mov_b32_e32 v138, v250
	v_mov_b32_e32 v139, v251
	global_load_dwordx4 v[248:251], v[214:215], off offset:2064
	v_pk_add_f32 v[126:127], v[126:127], v[138:139]
	v_pk_add_f32 v[124:125], v[124:125], v[136:137]
	v_readlane_b32 s94, v255, 27
	v_readlane_b32 s95, v255, 28
	s_waitcnt vmcnt(7)
	v_mov_b32_e32 v178, v228
	v_mov_b32_e32 v179, v229
	v_mov_b32_e32 v180, v230
	v_mov_b32_e32 v181, v231
	v_pk_add_f32 v[122:123], v[150:151], v[180:181]
	v_pk_add_f32 v[150:151], v[146:147], v[178:179]
	v_lshl_add_u64 v[146:147], v[120:121], 0, s[14:15]
	s_nop 0
	s_waitcnt vmcnt(6)
	v_mov_b32_e32 v140, v216
	v_mov_b32_e32 v141, v217
	v_mov_b32_e32 v142, v218
	v_mov_b32_e32 v143, v219
	v_pk_add_f32 v[126:127], v[126:127], v[142:143]
	v_pk_add_f32 v[124:125], v[124:125], v[140:141]
	s_waitcnt vmcnt(5)
	v_mov_b32_e32 v178, v224
	v_mov_b32_e32 v179, v225
	v_mov_b32_e32 v180, v226
	v_mov_b32_e32 v181, v227
	v_pk_add_f32 v[154:155], v[150:151], v[178:179]
	v_lshl_add_u64 v[150:151], v[120:121], 0, s[96:97]
	v_pk_add_f32 v[122:123], v[122:123], v[180:181]
	s_nop 0
	s_waitcnt vmcnt(4)
	v_mov_b32_e32 v144, v232
	v_mov_b32_e32 v145, v233
	v_mov_b32_e32 v146, v234
	v_mov_b32_e32 v147, v235
	v_pk_add_f32 v[126:127], v[126:127], v[146:147]
	v_pk_add_f32 v[124:125], v[124:125], v[144:145]
	s_mov_b32 s97, s39
	s_mov_b32 s96, s33
	s_waitcnt vmcnt(3)
	v_mov_b32_e32 v180, v236
	v_mov_b32_e32 v181, v237
	v_mov_b32_e32 v182, v238
	v_mov_b32_e32 v183, v239
	v_pk_add_f32 v[180:181], v[154:155], v[180:181]
	v_lshl_add_u64 v[154:155], v[120:121], 0, s[36:37]
	v_pk_add_f32 v[178:179], v[122:123], v[182:183]
	s_nop 0
	s_waitcnt vmcnt(2)
	v_mov_b32_e32 v148, v240
	v_mov_b32_e32 v149, v241
	v_mov_b32_e32 v150, v242
	v_mov_b32_e32 v151, v243
	v_pk_add_f32 v[126:127], v[126:127], v[150:151]
	v_pk_add_f32 v[124:125], v[124:125], v[148:149]
	s_waitcnt vmcnt(1)
	v_mov_b32_e32 v120, v244
	v_mov_b32_e32 v121, v245
	v_mov_b32_e32 v122, v246
	v_mov_b32_e32 v123, v247
	v_pk_add_f32 v[122:123], v[178:179], v[122:123]
	v_pk_add_f32 v[120:121], v[180:181], v[120:121]
	s_waitcnt vmcnt(0)
	v_mov_b32_e32 v152, v248
	v_mov_b32_e32 v153, v249
	v_mov_b32_e32 v154, v250
	v_mov_b32_e32 v155, v251
	v_pk_add_f32 v[126:127], v[126:127], v[154:155]
	v_pk_add_f32 v[124:125], v[124:125], v[152:153]

.LBB0_327:
	s_cmpk_gt_i32 s11, 0x43ff
	s_mov_b64 s[0:1], -1
	s_cbranch_scc1 .LBB0_321
	s_lshl_b32 s4, s11, 1
	s_cmpk_lt_i32 s11, 0x4000
	s_cselect_b64 s[0:1], -1, 0
	s_ashr_i32 s5, s4, 31
	s_add_i32 s30, s4, 0xffff8000
	s_cmpk_gt_i32 s11, 0x3fff
	s_cselect_b64 s[8:9], -1, 0
	s_and_b64 s[6:7], s[8:9], exec
	s_cselect_b32 s7, 0, s5
	s_cselect_b32 s6, s30, s4
	s_cselect_b32 s21, s99, s79
	s_cselect_b32 s24, s98, s78
	s_lshl_b64 s[22:23], s[6:7], 11
	s_add_u32 s22, s24, s22
	s_addc_u32 s23, s21, s23
	global_load_dwordx4 v[116:119], v170, s[22:23]
	global_load_dwordx4 v[112:115], v170, s[22:23] offset:1024
	global_load_dwordx4 v[108:111], v170, s[22:23] offset:2048
	global_load_dwordx4 v[104:107], v170, s[22:23] offset:3072
	s_and_b64 vcc, exec, s[0:1]
	s_cbranch_vccnz .LBB0_330
	s_lshl_b64 s[22:23], s[30:31], 12
	v_lshl_add_u64 v[88:89], v[176:177], 0, s[22:23]
	v_mov_b32_e32 v200, v88
	v_mov_b32_e32 v201, v89
	v_add_co_u32_e32 v202, vcc, 0x800000, v200
	s_nop 1
	v_addc_co_u32_e32 v203, vcc, 0, v201, vcc
	v_add_co_u32_e32 v204, vcc, 0x800000, v202
	s_nop 1
	v_addc_co_u32_e32 v205, vcc, 0, v203, vcc
	v_add_co_u32_e32 v206, vcc, 0x800000, v204
	s_nop 1
	v_addc_co_u32_e32 v207, vcc, 0, v205, vcc
	v_add_co_u32_e32 v208, vcc, 0x800000, v206
	s_nop 1
	v_addc_co_u32_e32 v209, vcc, 0, v207, vcc
	v_add_co_u32_e32 v210, vcc, 0x800000, v208
	s_nop 1
	v_addc_co_u32_e32 v211, vcc, 0, v209, vcc
	v_add_co_u32_e32 v212, vcc, 0x800000, v210
	s_nop 1
	v_addc_co_u32_e32 v213, vcc, 0, v211, vcc
	v_add_co_u32_e32 v214, vcc, 0x800000, v212
	s_nop 1
	v_addc_co_u32_e32 v215, vcc, 0, v213, vcc
	global_load_dwordx4 v[216:219], v[200:201], off offset:16
	global_load_dwordx4 v[224:227], v[200:201], off
	global_load_dwordx4 v[228:231], v[202:203], off
	global_load_dwordx4 v[232:235], v[202:203], off offset:16
	global_load_dwordx4 v[236:239], v[204:205], off
	global_load_dwordx4 v[240:243], v[204:205], off offset:16
	global_load_dwordx4 v[244:247], v[206:207], off
	global_load_dwordx4 v[248:251], v[206:207], off offset:16
	v_add_co_u32_e32 v96, vcc, 0x800000, v88
	s_mov_b64 s[24:25], 0x800000
	v_addc_co_u32_e32 v97, vcc, 0, v89, vcc
	v_lshl_add_u64 v[94:95], v[88:89], 0, s[24:25]
	s_mov_b64 s[26:27], 0x1000000
	v_add_co_u32_e32 v120, vcc, 0x1000000, v88
	s_mov_b64 s[28:29], 0x1800000
	s_nop 0
	v_addc_co_u32_e32 v121, vcc, 0, v89, vcc
	v_add_co_u32_e32 v122, vcc, 0x1800000, v88
	v_lshl_add_u64 v[100:101], v[88:89], 0, s[28:29]
	s_nop 0
	v_addc_co_u32_e32 v123, vcc, 0, v89, vcc
	v_add_co_u32_e32 v102, vcc, 0x2000000, v88
	s_mov_b64 s[34:35], 0x2000000
	s_nop 0
	v_addc_co_u32_e32 v103, vcc, 0, v89, vcc
	v_add_co_u32_e32 v124, vcc, 0x2800000, v88
	s_mov_b64 s[62:63], 0x2800000
	s_nop 0
	v_addc_co_u32_e32 v125, vcc, 0, v89, vcc
	s_mov_b64 s[64:65], 0x3000000
	v_lshl_add_u64 v[142:143], v[88:89], 0, s[64:65]
	s_mov_b64 s[68:69], 0x3800000
	v_lshl_add_u64 v[146:147], v[88:89], 0, s[68:69]
	s_mov_b64 s[70:71], 0x800800
	s_mov_b64 s[74:75], 0x1000800
	s_mov_b64 s[76:77], 0x1800800
	s_mov_b64 s[94:95], 0x2000800
	s_mov_b64 s[16:17], 0x2800800
	s_mov_b32 s38, s96
	s_mov_b64 s[96:97], 0x3000800
	s_mov_b64 s[36:37], 0x3800800
	s_add_i32 s30, s4, 0xffff8001
	s_lshl_b64 s[22:23], s[30:31], 12
	s_mov_b32 s21, 0x1000000
	s_waitcnt vmcnt(6)
	v_mov_b32_e32 v80, v224
	v_mov_b32_e32 v81, v225
	v_mov_b32_e32 v82, v226
	v_mov_b32_e32 v83, v227
	global_load_dwordx4 v[224:227], v[208:209], off
	s_waitcnt vmcnt(6)
	v_mov_b32_e32 v90, v228
	v_mov_b32_e32 v91, v229
	v_mov_b32_e32 v92, v230
	v_mov_b32_e32 v93, v231
	global_load_dwordx4 v[228:231], v[208:209], off offset:16
	v_pk_add_f32 v[98:99], v[82:83], v[92:93]
	v_lshl_add_u64 v[92:93], v[88:89], 0, s[26:27]
	v_pk_add_f32 v[90:91], v[80:81], v[90:91]
	s_nop 0
	s_waitcnt vmcnt(9)
	v_mov_b32_e32 v84, v216
	v_mov_b32_e32 v85, v217
	v_mov_b32_e32 v86, v218
	v_mov_b32_e32 v87, v219
	global_load_dwordx4 v[216:219], v[210:211], off
	s_waitcnt vmcnt(7)
	v_mov_b32_e32 v126, v232
	v_mov_b32_e32 v127, v233
	v_mov_b32_e32 v128, v234
	v_mov_b32_e32 v129, v235
	global_load_dwordx4 v[232:235], v[210:211], off offset:16
	v_pk_add_f32 v[86:87], v[86:87], v[128:129]
	v_pk_add_f32 v[84:85], v[84:85], v[126:127]
	s_waitcnt vmcnt(7)
	v_mov_b32_e32 v80, v236
	v_mov_b32_e32 v81, v237
	v_mov_b32_e32 v82, v238
	v_mov_b32_e32 v83, v239
	global_load_dwordx4 v[236:239], v[212:213], off
	v_pk_add_f32 v[98:99], v[98:99], v[82:83]
	v_pk_add_f32 v[90:91], v[90:91], v[80:81]
	v_lshl_add_u64 v[100:101], v[88:89], 0, s[34:35]
	s_waitcnt vmcnt(7)
	v_mov_b32_e32 v92, v240
	v_mov_b32_e32 v93, v241
	v_mov_b32_e32 v94, v242
	v_mov_b32_e32 v95, v243
	global_load_dwordx4 v[240:243], v[212:213], off offset:16
	v_pk_add_f32 v[86:87], v[86:87], v[94:95]
	v_pk_add_f32 v[84:85], v[84:85], v[92:93]
	s_waitcnt vmcnt(7)
	v_mov_b32_e32 v80, v244
	v_mov_b32_e32 v81, v245
	v_mov_b32_e32 v82, v246
	v_mov_b32_e32 v83, v247
	global_load_dwordx4 v[244:247], v[214:215], off
	v_pk_add_f32 v[98:99], v[98:99], v[82:83]
	v_pk_add_f32 v[90:91], v[90:91], v[80:81]
	v_lshl_add_u64 v[100:101], v[88:89], 0, s[62:63]
	s_waitcnt vmcnt(7)
	v_mov_b32_e32 v130, v248
	v_mov_b32_e32 v131, v249
	v_mov_b32_e32 v132, v250
	v_mov_b32_e32 v133, v251
	global_load_dwordx4 v[248:251], v[214:215], off offset:16
	v_pk_add_f32 v[86:87], v[86:87], v[132:133]
	v_pk_add_f32 v[84:85], v[84:85], v[130:131]
	s_waitcnt vmcnt(7)
	v_mov_b32_e32 v80, v224
	v_mov_b32_e32 v81, v225
	v_mov_b32_e32 v82, v226
	v_mov_b32_e32 v83, v227
	global_load_dwordx4 v[224:227], v[200:201], off offset:2064
	v_pk_add_f32 v[98:99], v[98:99], v[82:83]
	v_pk_add_f32 v[90:91], v[90:91], v[80:81]
	v_add_co_u32_e32 v100, vcc, 0x3000000, v88
	s_waitcnt vmcnt(7)
	v_mov_b32_e32 v134, v228
	v_mov_b32_e32 v135, v229
	v_mov_b32_e32 v136, v230
	v_mov_b32_e32 v137, v231
	global_load_dwordx4 v[228:231], v[200:201], off offset:2048
	v_pk_add_f32 v[86:87], v[86:87], v[136:137]
	v_addc_co_u32_e32 v101, vcc, 0, v89, vcc
	v_pk_add_f32 v[84:85], v[84:85], v[134:135]
	s_waitcnt vmcnt(7)
	v_mov_b32_e32 v80, v216
	v_mov_b32_e32 v81, v217
	v_mov_b32_e32 v82, v218
	v_mov_b32_e32 v83, v219
	global_load_dwordx4 v[216:219], v[202:203], off offset:2048
	v_pk_add_f32 v[98:99], v[98:99], v[82:83]
	v_pk_add_f32 v[90:91], v[90:91], v[80:81]
	s_nop 0
	s_waitcnt vmcnt(7)
	v_mov_b32_e32 v138, v232
	v_mov_b32_e32 v139, v233
	v_mov_b32_e32 v140, v234
	v_mov_b32_e32 v141, v235
	global_load_dwordx4 v[232:235], v[202:203], off offset:2064
	v_pk_add_f32 v[84:85], v[84:85], v[138:139]
	v_pk_add_f32 v[86:87], v[86:87], v[140:141]
	s_waitcnt vmcnt(7)
	v_mov_b32_e32 v80, v236
	v_mov_b32_e32 v81, v237
	v_mov_b32_e32 v82, v238
	v_mov_b32_e32 v83, v239
	global_load_dwordx4 v[236:239], v[204:205], off offset:2048
	v_pk_add_f32 v[150:151], v[90:91], v[80:81]
	v_add_co_u32_e32 v90, vcc, 0x3800000, v88
	v_pk_add_f32 v[98:99], v[98:99], v[82:83]
	s_nop 0
	v_addc_co_u32_e32 v91, vcc, 0, v89, vcc
	s_nop 0
	s_nop 0
	s_waitcnt vmcnt(7)
	v_mov_b32_e32 v142, v240
	v_mov_b32_e32 v143, v241
	v_mov_b32_e32 v144, v242
	v_mov_b32_e32 v145, v243
	global_load_dwordx4 v[240:243], v[204:205], off offset:2064
	v_pk_add_f32 v[84:85], v[84:85], v[142:143]
	v_pk_add_f32 v[86:87], v[86:87], v[144:145]
	s_waitcnt vmcnt(7)
	v_mov_b32_e32 v80, v244
	v_mov_b32_e32 v81, v245
	v_mov_b32_e32 v82, v246
	v_mov_b32_e32 v83, v247
	global_load_dwordx4 v[244:247], v[206:207], off offset:2048
	v_pk_add_f32 v[82:83], v[98:99], v[82:83]
	v_lshl_add_u64 v[98:99], v[88:89], 0, s[70:71]
	s_nop 0
	s_waitcnt vmcnt(7)
	v_mov_b32_e32 v146, v248
	v_mov_b32_e32 v147, v249
	v_mov_b32_e32 v148, v250
	v_mov_b32_e32 v149, v251
	global_load_dwordx4 v[248:251], v[206:207], off offset:2064
	v_pk_add_f32 v[86:87], v[86:87], v[148:149]
	v_pk_add_f32 v[84:85], v[84:85], v[146:147]
	v_pk_add_f32 v[80:81], v[150:151], v[80:81]
	s_waitcnt vmcnt(6)
	v_mov_b32_e32 v126, v228
	v_mov_b32_e32 v127, v229
	v_mov_b32_e32 v128, v230
	v_mov_b32_e32 v129, v231
	global_load_dwordx4 v[228:231], v[208:209], off offset:2048
	s_waitcnt vmcnt(6)
	v_mov_b32_e32 v130, v216
	v_mov_b32_e32 v131, v217
	v_mov_b32_e32 v132, v218
	v_mov_b32_e32 v133, v219
	global_load_dwordx4 v[216:219], v[208:209], off offset:2064
	v_pk_add_f32 v[136:137], v[126:127], v[130:131]
	v_lshl_add_u64 v[130:131], v[88:89], 0, s[74:75]
	v_pk_add_f32 v[134:135], v[128:129], v[132:133]
	s_nop 0
	s_waitcnt vmcnt(9)
	v_mov_b32_e32 v92, v224
	v_mov_b32_e32 v93, v225
	v_mov_b32_e32 v94, v226
	v_mov_b32_e32 v95, v227
	global_load_dwordx4 v[224:227], v[210:211], off offset:2048
	s_waitcnt vmcnt(7)
	v_mov_b32_e32 v96, v232
	v_mov_b32_e32 v97, v233
	v_mov_b32_e32 v98, v234
	v_mov_b32_e32 v99, v235
	global_load_dwordx4 v[232:235], v[210:211], off offset:2064
	v_pk_add_f32 v[92:93], v[92:93], v[96:97]
	v_pk_add_f32 v[94:95], v[94:95], v[98:99]
	s_waitcnt vmcnt(7)
	v_mov_b32_e32 v126, v236
	v_mov_b32_e32 v127, v237
	v_mov_b32_e32 v128, v238
	v_mov_b32_e32 v129, v239
	global_load_dwordx4 v[236:239], v[212:213], off offset:2048
	v_pk_add_f32 v[136:137], v[136:137], v[126:127]
	v_lshl_add_u64 v[126:127], v[88:89], 0, s[76:77]
	v_pk_add_f32 v[134:135], v[134:135], v[128:129]
	s_nop 0
	s_waitcnt vmcnt(7)
	v_mov_b32_e32 v130, v240
	v_mov_b32_e32 v131, v241
	v_mov_b32_e32 v132, v242
	v_mov_b32_e32 v133, v243
	global_load_dwordx4 v[240:243], v[212:213], off offset:2064
	v_pk_add_f32 v[92:93], v[92:93], v[130:131]
	v_pk_add_f32 v[94:95], v[94:95], v[132:133]
	s_waitcnt vmcnt(7)
	v_mov_b32_e32 v120, v244
	v_mov_b32_e32 v121, v245
	v_mov_b32_e32 v122, v246
	v_mov_b32_e32 v123, v247
	global_load_dwordx4 v[244:247], v[214:215], off offset:2048
	v_pk_add_f32 v[138:139], v[134:135], v[122:123]
	v_lshl_add_u64 v[134:135], v[88:89], 0, s[94:95]
	v_pk_add_f32 v[140:141], v[136:137], v[120:121]
	s_nop 0
	s_waitcnt vmcnt(7)
	v_mov_b32_e32 v126, v248
	v_mov_b32_e32 v127, v249
	v_mov_b32_e32 v128, v250
	v_mov_b32_e32 v129, v251
	global_load_dwordx4 v[248:251], v[214:215], off offset:2064
	v_pk_add_f32 v[92:93], v[92:93], v[126:127]
	v_pk_add_f32 v[94:95], v[94:95], v[128:129]
	s_waitcnt vmcnt(7)
	v_mov_b32_e32 v120, v228
	v_mov_b32_e32 v121, v229
	v_mov_b32_e32 v122, v230
	v_mov_b32_e32 v123, v231
	v_pk_add_f32 v[102:103], v[138:139], v[122:123]
	v_lshl_add_u64 v[138:139], v[88:89], 0, s[16:17]
	v_pk_add_f32 v[142:143], v[140:141], v[120:121]
	s_nop 0
	s_waitcnt vmcnt(6)
	v_mov_b32_e32 v134, v216
	v_mov_b32_e32 v135, v217
	v_mov_b32_e32 v136, v218
	v_mov_b32_e32 v137, v219
	v_pk_add_f32 v[92:93], v[92:93], v[134:135]
	v_pk_add_f32 v[94:95], v[94:95], v[136:137]
	s_waitcnt vmcnt(5)
	v_mov_b32_e32 v120, v224
	v_mov_b32_e32 v121, v225
	v_mov_b32_e32 v122, v226
	v_mov_b32_e32 v123, v227
	v_pk_add_f32 v[142:143], v[142:143], v[120:121]
	v_lshl_add_u64 v[120:121], v[88:89], 0, s[96:97]
	v_pk_add_f32 v[124:125], v[102:103], v[122:123]
	s_nop 0
	s_waitcnt vmcnt(4)
	v_mov_b32_e32 v138, v232
	v_mov_b32_e32 v139, v233
	v_mov_b32_e32 v140, v234
	v_mov_b32_e32 v141, v235
	v_pk_add_f32 v[92:93], v[92:93], v[138:139]
	v_pk_add_f32 v[94:95], v[94:95], v[140:141]
	s_waitcnt vmcnt(3)
	v_mov_b32_e32 v100, v236
	v_mov_b32_e32 v101, v237
	v_mov_b32_e32 v102, v238
	v_mov_b32_e32 v103, v239
	v_pk_add_f32 v[142:143], v[142:143], v[100:101]
	v_lshl_add_u64 v[100:101], v[88:89], 0, s[36:37]
	v_pk_add_f32 v[124:125], v[124:125], v[102:103]
	s_nop 0
	s_waitcnt vmcnt(2)
	v_mov_b32_e32 v120, v240
	v_mov_b32_e32 v121, v241
	v_mov_b32_e32 v122, v242
	v_mov_b32_e32 v123, v243
	v_pk_add_f32 v[92:93], v[92:93], v[120:121]
	v_lshl_add_u64 v[120:121], v[176:177], 0, s[22:23]
	v_pk_add_f32 v[94:95], v[94:95], v[122:123]
	v_add_co_u32_e32 v122, vcc, s55, v120
	v_lshl_add_u64 v[128:129], v[120:121], 0, s[24:25]
	s_nop 0
	v_addc_co_u32_e32 v123, vcc, 0, v121, vcc
	v_add_co_u32_e32 v132, vcc, s21, v120
	s_mov_b32 s21, 0x1800000
	s_nop 0
	v_addc_co_u32_e32 v133, vcc, 0, v121, vcc
	v_lshl_add_u64 v[140:141], v[120:121], 0, s[28:29]
	s_waitcnt vmcnt(1)
	v_mov_b32_e32 v88, v244
	v_mov_b32_e32 v89, v245
	v_mov_b32_e32 v90, v246
	v_mov_b32_e32 v91, v247
	v_pk_add_f32 v[90:91], v[124:125], v[90:91]
	s_waitcnt vmcnt(0)
	v_mov_b32_e32 v100, v248
	v_mov_b32_e32 v101, v249
	v_mov_b32_e32 v102, v250
	v_mov_b32_e32 v103, v251
	v_pk_add_f32 v[94:95], v[94:95], v[102:103]
	v_pk_add_f32 v[92:93], v[92:93], v[100:101]
	v_add_co_u32_e32 v200, vcc, 0x1000, v200
	s_nop 1
	v_addc_co_u32_e32 v201, vcc, 0, v201, vcc
	v_add_co_u32_e32 v202, vcc, 0x1000, v202
	s_nop 1
	v_addc_co_u32_e32 v203, vcc, 0, v203, vcc
	v_add_co_u32_e32 v204, vcc, 0x1000, v204
	s_nop 1
	v_addc_co_u32_e32 v205, vcc, 0, v205, vcc
	v_add_co_u32_e32 v206, vcc, 0x1000, v206
	s_nop 1
	v_addc_co_u32_e32 v207, vcc, 0, v207, vcc
	v_add_co_u32_e32 v208, vcc, 0x1000, v208
	s_nop 1
	v_addc_co_u32_e32 v209, vcc, 0, v209, vcc
	v_add_co_u32_e32 v210, vcc, 0x1000, v210
	s_nop 1
	v_addc_co_u32_e32 v211, vcc, 0, v211, vcc
	v_add_co_u32_e32 v212, vcc, 0x1000, v212
	s_nop 1
	v_addc_co_u32_e32 v213, vcc, 0, v213, vcc
	v_add_co_u32_e32 v214, vcc, 0x1000, v214
	s_nop 1
	v_addc_co_u32_e32 v215, vcc, 0, v215, vcc
	global_load_dwordx4 v[216:219], v[200:201], off offset:16
	global_load_dwordx4 v[224:227], v[200:201], off
	global_load_dwordx4 v[228:231], v[202:203], off
	global_load_dwordx4 v[232:235], v[202:203], off offset:16
	global_load_dwordx4 v[236:239], v[204:205], off
	global_load_dwordx4 v[240:243], v[204:205], off offset:16
	global_load_dwordx4 v[244:247], v[206:207], off
	global_load_dwordx4 v[248:251], v[206:207], off offset:16
	s_nop 0
	v_pk_add_f32 v[88:89], v[142:143], v[88:89]
	v_lshl_add_u64 v[142:143], v[120:121], 0, s[34:35]
	s_waitcnt vmcnt(6)
	v_mov_b32_e32 v96, v224
	v_mov_b32_e32 v97, v225
	v_mov_b32_e32 v98, v226
	v_mov_b32_e32 v99, v227
	global_load_dwordx4 v[224:227], v[208:209], off
	s_waitcnt vmcnt(6)
	v_mov_b32_e32 v124, v228
	v_mov_b32_e32 v125, v229
	v_mov_b32_e32 v126, v230
	v_mov_b32_e32 v127, v231
	global_load_dwordx4 v[228:231], v[208:209], off offset:16
	v_pk_add_f32 v[136:137], v[96:97], v[124:125]
	v_lshl_add_u64 v[124:125], v[120:121], 0, s[26:27]
	v_pk_add_f32 v[134:135], v[98:99], v[126:127]
	s_nop 0
	s_waitcnt vmcnt(9)
	v_mov_b32_e32 v100, v216
	v_mov_b32_e32 v101, v217
	v_mov_b32_e32 v102, v218
	v_mov_b32_e32 v103, v219
	global_load_dwordx4 v[216:219], v[210:211], off
	s_waitcnt vmcnt(7)
	v_mov_b32_e32 v128, v232
	v_mov_b32_e32 v129, v233
	v_mov_b32_e32 v130, v234
	v_mov_b32_e32 v131, v235
	global_load_dwordx4 v[232:235], v[210:211], off offset:16
	v_pk_add_f32 v[102:103], v[102:103], v[130:131]
	v_pk_add_f32 v[100:101], v[100:101], v[128:129]
	v_lshl_add_u64 v[128:129], v[120:121], 0, s[70:71]
	s_waitcnt vmcnt(7)
	v_mov_b32_e32 v96, v236
	v_mov_b32_e32 v97, v237
	v_mov_b32_e32 v98, v238
	v_mov_b32_e32 v99, v239
	global_load_dwordx4 v[236:239], v[212:213], off
	v_pk_add_f32 v[138:139], v[136:137], v[96:97]
	v_add_co_u32_e32 v136, vcc, s21, v120
	v_pk_add_f32 v[134:135], v[134:135], v[98:99]
	s_nop 0
	v_addc_co_u32_e32 v137, vcc, 0, v121, vcc
	s_brev_b32 s21, 64
	v_add_co_u32_e32 v140, vcc, s21, v120
	s_mov_b32 s21, 0x2800000
	s_nop 0
	v_addc_co_u32_e32 v141, vcc, 0, v121, vcc
	v_add_co_u32_e32 v144, vcc, s21, v120
	s_mov_b32 s21, 0x3000000
	s_nop 0
	v_addc_co_u32_e32 v145, vcc, 0, v121, vcc
	v_add_co_u32_e32 v148, vcc, s21, v120
	s_mov_b32 s21, 0x3800000
	s_nop 0
	v_addc_co_u32_e32 v149, vcc, 0, v121, vcc
	v_add_co_u32_e32 v152, vcc, s21, v120
	s_waitcnt vmcnt(7)
	v_mov_b32_e32 v124, v240
	v_mov_b32_e32 v125, v241
	v_mov_b32_e32 v126, v242
	v_mov_b32_e32 v127, v243
	global_load_dwordx4 v[240:243], v[212:213], off offset:16
	v_pk_add_f32 v[102:103], v[102:103], v[126:127]
	v_addc_co_u32_e32 v153, vcc, 0, v121, vcc
	v_pk_add_f32 v[100:101], v[100:101], v[124:125]
	s_waitcnt vmcnt(7)
	v_mov_b32_e32 v96, v244
	v_mov_b32_e32 v97, v245
	v_mov_b32_e32 v98, v246
	v_mov_b32_e32 v99, v247
	global_load_dwordx4 v[244:247], v[214:215], off
	v_pk_add_f32 v[134:135], v[134:135], v[98:99]
	v_pk_add_f32 v[138:139], v[138:139], v[96:97]
	v_lshl_add_u64 v[142:143], v[120:121], 0, s[62:63]
	s_waitcnt vmcnt(7)
	v_mov_b32_e32 v178, v248
	v_mov_b32_e32 v179, v249
	v_mov_b32_e32 v180, v250
	v_mov_b32_e32 v181, v251
	global_load_dwordx4 v[248:251], v[214:215], off offset:16
	v_pk_add_f32 v[102:103], v[102:103], v[180:181]
	v_pk_add_f32 v[100:101], v[100:101], v[178:179]
	s_waitcnt vmcnt(7)
	v_mov_b32_e32 v96, v224
	v_mov_b32_e32 v97, v225
	v_mov_b32_e32 v98, v226
	v_mov_b32_e32 v99, v227
	global_load_dwordx4 v[224:227], v[200:201], off offset:2064
	v_pk_add_f32 v[134:135], v[134:135], v[98:99]
	v_pk_add_f32 v[138:139], v[138:139], v[96:97]
	v_lshl_add_u64 v[142:143], v[120:121], 0, s[64:65]
	s_waitcnt vmcnt(7)
	v_mov_b32_e32 v182, v228
	v_mov_b32_e32 v183, v229
	v_mov_b32_e32 v184, v230
	v_mov_b32_e32 v185, v231
	global_load_dwordx4 v[228:231], v[200:201], off offset:2048
	v_pk_add_f32 v[102:103], v[102:103], v[184:185]
	v_pk_add_f32 v[100:101], v[100:101], v[182:183]
	s_waitcnt vmcnt(7)
	v_mov_b32_e32 v96, v216
	v_mov_b32_e32 v97, v217
	v_mov_b32_e32 v98, v218
	v_mov_b32_e32 v99, v219
	global_load_dwordx4 v[216:219], v[202:203], off offset:2048
	v_pk_add_f32 v[134:135], v[134:135], v[98:99]
	v_pk_add_f32 v[138:139], v[138:139], v[96:97]
	v_lshl_add_u64 v[142:143], v[120:121], 0, s[68:69]
	s_waitcnt vmcnt(7)
	v_mov_b32_e32 v186, v232
	v_mov_b32_e32 v187, v233
	v_mov_b32_e32 v188, v234
	v_mov_b32_e32 v189, v235
	global_load_dwordx4 v[232:235], v[202:203], off offset:2064
	v_pk_add_f32 v[102:103], v[102:103], v[188:189]
	v_pk_add_f32 v[100:101], v[100:101], v[186:187]
	s_waitcnt vmcnt(7)
	v_mov_b32_e32 v96, v236
	v_mov_b32_e32 v97, v237
	v_mov_b32_e32 v98, v238
	v_mov_b32_e32 v99, v239
	global_load_dwordx4 v[236:239], v[204:205], off offset:2048
	v_pk_add_f32 v[134:135], v[134:135], v[98:99]
	v_pk_add_f32 v[138:139], v[138:139], v[96:97]
	s_nop 0
	s_waitcnt vmcnt(7)
	v_mov_b32_e32 v190, v240
	v_mov_b32_e32 v191, v241
	v_mov_b32_e32 v192, v242
	v_mov_b32_e32 v193, v243
	global_load_dwordx4 v[240:243], v[204:205], off offset:2064
	v_pk_add_f32 v[102:103], v[102:103], v[192:193]
	v_pk_add_f32 v[100:101], v[100:101], v[190:191]
	s_waitcnt vmcnt(7)
	v_mov_b32_e32 v96, v244
	v_mov_b32_e32 v97, v245
	v_mov_b32_e32 v98, v246
	v_mov_b32_e32 v99, v247
	global_load_dwordx4 v[244:247], v[206:207], off offset:2048
	v_pk_add_f32 v[98:99], v[134:135], v[98:99]
	v_lshl_add_u64 v[134:135], v[120:121], 0, s[74:75]
	v_pk_add_f32 v[96:97], v[138:139], v[96:97]
	s_waitcnt vmcnt(5)
	v_mov_b32_e32 v178, v228
	v_mov_b32_e32 v179, v229
	v_mov_b32_e32 v180, v230
	v_mov_b32_e32 v181, v231
	global_load_dwordx4 v[228:231], v[206:207], off offset:2064
	s_waitcnt vmcnt(5)
	v_mov_b32_e32 v182, v216
	v_mov_b32_e32 v183, v217
	v_mov_b32_e32 v184, v218
	v_mov_b32_e32 v185, v219
	global_load_dwordx4 v[216:219], v[208:209], off offset:2048
	v_pk_add_f32 v[122:123], v[180:181], v[184:185]
	v_pk_add_f32 v[138:139], v[178:179], v[182:183]
	s_nop 0
	s_waitcnt vmcnt(8)
	v_mov_b32_e32 v124, v224
	v_mov_b32_e32 v125, v225
	v_mov_b32_e32 v126, v226
	v_mov_b32_e32 v127, v227
	global_load_dwordx4 v[224:227], v[208:209], off offset:2064
	s_waitcnt vmcnt(6)
	v_mov_b32_e32 v128, v232
	v_mov_b32_e32 v129, v233
	v_mov_b32_e32 v130, v234
	v_mov_b32_e32 v131, v235
	global_load_dwordx4 v[232:235], v[210:211], off offset:2048
	v_pk_add_f32 v[126:127], v[126:127], v[130:131]
	v_pk_add_f32 v[124:125], v[124:125], v[128:129]
	s_waitcnt vmcnt(11)
	v_mov_b32_e32 v194, v248
	v_mov_b32_e32 v195, v249
	v_mov_b32_e32 v196, v250
	v_mov_b32_e32 v197, v251
	global_load_dwordx4 v[248:251], v[210:211], off offset:2064
	v_pk_add_f32 v[102:103], v[102:103], v[196:197]
	v_pk_add_f32 v[100:101], v[100:101], v[194:195]
	s_waitcnt vmcnt(7)
	v_mov_b32_e32 v178, v236
	v_mov_b32_e32 v179, v237
	v_mov_b32_e32 v180, v238
	v_mov_b32_e32 v181, v239
	global_load_dwordx4 v[236:239], v[212:213], off offset:2048
	v_pk_add_f32 v[142:143], v[138:139], v[178:179]
	v_lshl_add_u64 v[138:139], v[120:121], 0, s[76:77]
	v_pk_add_f32 v[122:123], v[122:123], v[180:181]
	s_nop 0
	s_waitcnt vmcnt(7)
	v_mov_b32_e32 v132, v240
	v_mov_b32_e32 v133, v241
	v_mov_b32_e32 v134, v242
	v_mov_b32_e32 v135, v243
	global_load_dwordx4 v[240:243], v[212:213], off offset:2064
	v_pk_add_f32 v[126:127], v[126:127], v[134:135]
	v_pk_add_f32 v[124:125], v[124:125], v[132:133]
	s_waitcnt vmcnt(7)
	v_mov_b32_e32 v178, v244
	v_mov_b32_e32 v179, v245
	v_mov_b32_e32 v180, v246
	v_mov_b32_e32 v181, v247
	global_load_dwordx4 v[244:247], v[214:215], off offset:2048
	v_pk_add_f32 v[146:147], v[142:143], v[178:179]
	v_lshl_add_u64 v[142:143], v[120:121], 0, s[94:95]
	v_pk_add_f32 v[122:123], v[122:123], v[180:181]
	s_nop 0
	s_waitcnt vmcnt(7)
	v_mov_b32_e32 v136, v228
	v_mov_b32_e32 v137, v229
	v_mov_b32_e32 v138, v230
	v_mov_b32_e32 v139, v231
	global_load_dwordx4 v[228:231], v[214:215], off offset:2064
	v_pk_add_f32 v[126:127], v[126:127], v[138:139]
	v_pk_add_f32 v[124:125], v[124:125], v[136:137]
	v_readlane_b32 s94, v255, 27
	v_readlane_b32 s95, v255, 28
	s_waitcnt vmcnt(7)
	v_mov_b32_e32 v178, v216
	v_mov_b32_e32 v179, v217
	v_mov_b32_e32 v180, v218
	v_mov_b32_e32 v181, v219
	v_pk_add_f32 v[150:151], v[146:147], v[178:179]
	v_lshl_add_u64 v[146:147], v[120:121], 0, s[16:17]
	v_pk_add_f32 v[122:123], v[122:123], v[180:181]
	s_nop 0
	s_waitcnt vmcnt(6)
	v_mov_b32_e32 v140, v224
	v_mov_b32_e32 v141, v225
	v_mov_b32_e32 v142, v226
	v_mov_b32_e32 v143, v227
	v_pk_add_f32 v[126:127], v[126:127], v[142:143]
	v_pk_add_f32 v[124:125], v[124:125], v[140:141]
	s_waitcnt vmcnt(5)
	v_mov_b32_e32 v178, v232
	v_mov_b32_e32 v179, v233
	v_mov_b32_e32 v180, v234
	v_mov_b32_e32 v181, v235
	v_pk_add_f32 v[154:155], v[150:151], v[178:179]
	v_lshl_add_u64 v[150:151], v[120:121], 0, s[96:97]
	v_pk_add_f32 v[122:123], v[122:123], v[180:181]
	s_nop 0
	s_waitcnt vmcnt(4)
	v_mov_b32_e32 v144, v248
	v_mov_b32_e32 v145, v249
	v_mov_b32_e32 v146, v250
	v_mov_b32_e32 v147, v251
	v_pk_add_f32 v[126:127], v[126:127], v[146:147]
	v_pk_add_f32 v[124:125], v[124:125], v[144:145]
	s_mov_b32 s96, s38
	s_waitcnt vmcnt(3)
	v_mov_b32_e32 v180, v236
	v_mov_b32_e32 v181, v237
	v_mov_b32_e32 v182, v238
	v_mov_b32_e32 v183, v239
	v_pk_add_f32 v[180:181], v[154:155], v[180:181]
	v_lshl_add_u64 v[154:155], v[120:121], 0, s[36:37]
	v_pk_add_f32 v[178:179], v[122:123], v[182:183]
	s_nop 0
	s_waitcnt vmcnt(2)
	v_mov_b32_e32 v148, v240
	v_mov_b32_e32 v149, v241
	v_mov_b32_e32 v150, v242
	v_mov_b32_e32 v151, v243
	v_pk_add_f32 v[126:127], v[126:127], v[150:151]
	v_pk_add_f32 v[124:125], v[124:125], v[148:149]
	s_waitcnt vmcnt(1)
	v_mov_b32_e32 v120, v244
	v_mov_b32_e32 v121, v245
	v_mov_b32_e32 v122, v246
	v_mov_b32_e32 v123, v247
	v_pk_add_f32 v[122:123], v[178:179], v[122:123]
	v_pk_add_f32 v[120:121], v[180:181], v[120:121]
	s_waitcnt vmcnt(0)
	v_mov_b32_e32 v152, v228
	v_mov_b32_e32 v153, v229
	v_mov_b32_e32 v154, v230
	v_mov_b32_e32 v155, v231
	v_pk_add_f32 v[126:127], v[126:127], v[154:155]
	v_pk_add_f32 v[124:125], v[124:125], v[152:153]
